# static s_setprio 1 for waves 0-3 (older half) inside the global attention loop
# speedup vs baseline: 1.0044x; 1.0010x over previous
; __device__ __forceinline__ void attn_global(LAS unsigned char* lds, const bf16_t* __restrict__ PROJ, const bf16_t* __restrict__ VT, bf16_t* __restrict__ AO,
;                                             int rowbase, int S, int hq, int q0, float bound2) {
;     ...
;     int t = 0;
; #pragma unroll 1
;     for (; t + 10 < T; t += 4) { ATT_DSTEP(t, 0, true); ATT_DSTEP(t + 2, 2, true); }
; #pragma unroll 1
;     for (; t < T; t += 4) { ATT_DSTEP(t, 0, false); ATT_DSTEP(t + 2, 2, false); }
.LBB0_206:
	v_readfirstlane_b32 s98, v171
	s_nop 3
	s_cmpk_lt_u32 s98, 0x100
	s_cbranch_scc0 .Lattn_noprio
	s_setprio 1

; __device__ __forceinline__ void attn_global(LAS unsigned char* lds, const bf16_t* __restrict__ PROJ, const bf16_t* __restrict__ VT, bf16_t* __restrict__ AO,
;                                             int rowbase, int S, int hq, int q0, float bound2) {
;     ...
;     for (; t + 10 < T; t += 4) { ATT_DSTEP(t, 0, true); ATT_DSTEP(t + 2, 2, true); }
; #pragma unroll 1
;     for (; t < T; t += 4) { ATT_DSTEP(t, 0, false); ATT_DSTEP(t + 2, 2, false); }
.Lattn_exit:
	s_setprio 0
	s_waitcnt lgkmcnt(0)
	s_add_i32 s6, s6, -10
	s_cmp_ge_u32 s6, s82
	s_cbranch_scc1 .LBB0_251
